# mixer: workgroups with original blockIdx >= 256 run the deferred conversions before their attention items (others after), splitting the conversion traffic in two and pairing a memory-bound with a comp
# speedup vs baseline: 1.0096x; 1.0095x over previous
; __device__ __forceinline__ int tid_() { int t = threadIdx.x; asm volatile("" : "+v"(t)); return t; }
; __device__ void ph_mixer(const P& p, u16* lds) {
;   const int NSCAN = 32;
;     ...
;   if ((int)blockIdx.x < NSCAN) { if (MIXMASK & 1) scan_seq(p, blockIdx.x, lds); return; }
;   const int NA = 2048, NSA = 256, NSD = 256, NCP = 2409;
;   const int st = gridDim.x - NSCAN, b0 = blockIdx.x - NSCAN;
;   auto first = [&](int off) { int f = b0 - (off % st); return f < 0 ? f + st : f; };
;   if (MIXMASK & 8) for (int it = first(0); it < NSD; it += st) dn_sample_wave(p, it * 4 + (tid_() >> 6));
;   if (MIXMASK & 4) for (int it = first(224); it < NSA; it += st) attn_sample_item(p, it, lds);
;   if (MIXMASK & 2) for (int it = first(288); it < NA; it += st) attn_prompt_item(p, it, lds);
;   if (MIXMASK & 16) for (int it = first(256); it < NCP; it += st) copy_item(p, it);
; }
.Lmx_orig:
	v_readlane_b32 s0, v227, 60
	s_mov_b32 s1, 0
	s_nop 0
	v_writelane_b32 v227, s1, 62
	s_cmpk_lt_u32 s0, 0x100
	s_cbranch_scc1 .Lmx_late
	s_mov_b32 s1, 1
	s_nop 0
	v_writelane_b32 v227, s1, 62
	s_mov_b32 s64, 1
	s_branch .Ldef_entry

; __device__ __forceinline__ int tid_() { int t = threadIdx.x; asm volatile("" : "+v"(t)); return t; }
; __device__ void ph_mixer(const P& p, u16* lds) {
;     ...
;   if ((int)blockIdx.x < NSCAN) { if (MIXMASK & 1) scan_seq(p, blockIdx.x, lds); return; }
;   const int NA = 2048, NSA = 256, NSD = 256, NCP = 2409;
;   const int st = gridDim.x - NSCAN, b0 = blockIdx.x - NSCAN;
;   auto first = [&](int off) { int f = b0 - (off % st); return f < 0 ? f + st : f; };
;   if (MIXMASK & 8) for (int it = first(0); it < NSD; it += st) dn_sample_wave(p, it * 4 + (tid_() >> 6));
;   if (MIXMASK & 4) for (int it = first(224); it < NSA; it += st) attn_sample_item(p, it, lds);
;   if (MIXMASK & 2) for (int it = first(288); it < NA; it += st) attn_prompt_item(p, it, lds);
;   if (MIXMASK & 16) for (int it = first(256); it < NCP; it += st) copy_item(p, it);
.LBB0_478:
	s_and_b64 vcc, exec, s[0:1]
	s_cbranch_vccnz .Lscan_go
	v_readlane_b32 s0, v227, 62
	s_mov_b32 s64, 0
	s_nop 0
	s_cmp_eq_u32 s0, 1
	s_cbranch_scc1 .LBB0_485
.Ldef_entry:
	v_readlane_b32 s50, v228, 0
	v_readlane_b32 s51, v228, 10
	v_readlane_b32 s40, v228, 8
	v_readlane_b32 s41, v228, 9
	v_readlane_b32 s42, v228, 57
	v_readlane_b32 s43, v228, 58
	v_readlane_b32 s44, v228, 59
	v_readlane_b32 s45, v228, 60
	v_readlane_b32 s46, v228, 21
	v_readlane_b32 s47, v228, 22
	v_readlane_b32 s48, v228, 23
	v_readlane_b32 s49, v228, 24
	s_sub_u32 s50, s50, 32
	s_sub_u32 s51, s51, 32
	v_lshlrev_b32_e32 v1, 5, v220
	v_add_u32_e32 v5, 0x2000, v1
	v_add_u32_e32 v6, 0x4000, v1
	v_add_u32_e32 v7, 0x6000, v1
	v_lshlrev_b32_e32 v3, 4, v220
	v_add_u32_e32 v9, 0x1000, v3
	v_add_u32_e32 v10, 0x2000, v3
	v_add_u32_e32 v11, 0x3000, v3
	v_bfe_u32 v2, v220, 4, 3
	v_lshlrev_b32_e32 v2, 21, v2
	v_lshrrev_b32_e32 v12, 7, v220
	v_lshl_or_b32 v2, v12, 7, v2
	v_and_b32_e32 v12, 15, v220
	v_lshl_or_b32 v2, v12, 3, v2
	v_mov_b32_e32 v13, 0

; __device__ __forceinline__ int tid_() { int t = threadIdx.x; asm volatile("" : "+v"(t)); return t; }
; __device__ void ph_mixer(const P& p, u16* lds) {
;     ...
;   if ((int)blockIdx.x < NSCAN) { if (MIXMASK & 1) scan_seq(p, blockIdx.x, lds); return; }
;   const int NA = 2048, NSA = 256, NSD = 256, NCP = 2409;
;   const int st = gridDim.x - NSCAN, b0 = blockIdx.x - NSCAN;
;   auto first = [&](int off) { int f = b0 - (off % st); return f < 0 ? f + st : f; };
;   if (MIXMASK & 8) for (int it = first(0); it < NSD; it += st) dn_sample_wave(p, it * 4 + (tid_() >> 6));
;   if (MIXMASK & 4) for (int it = first(224); it < NSA; it += st) attn_sample_item(p, it, lds);
;   if (MIXMASK & 2) for (int it = first(288); it < NA; it += st) attn_prompt_item(p, it, lds);
;   if (MIXMASK & 16) for (int it = first(256); it < NCP; it += st) copy_item(p, it);
; }
.Ldef_done:
	s_cmp_eq_u32 s64, 1
	s_cbranch_scc1 .Lmx_late
	s_branch .LBB0_485
